# P0b transposes loop: wait for the next tiles' prefetch loads just before this iteration's first store instead of immediately after issuing them
# speedup vs baseline: 1.0046x; 1.0046x over previous
; #define LAUNDER(v) asm volatile("" : "+s"(v))
; __device__ __forceinline__ int vtid() { int t = threadIdx.x; asm volatile("" : "+v"(t)); return t; }
; __device__ __forceinline__ void tr_lds_write(float* tile, int tid, const float4 (&r)[4]) {
;   const int c4 = tid & 15, rr = tid >> 4;
; #pragma unroll
;   for (int pp = 0; pp < 4; ++pp) {
;     float* t = &tile[(rr + 16 * pp) * 65 + c4 * 4];
;     t[0] = r[pp].x; t[1] = r[pp].y; t[2] = r[pp].z; t[3] = r[pp].w;
;   }
; }
; __device__ __forceinline__ void tr_store(const Params& p, char* ws, int job, int tid, const float* tile) {
;   TrJob t = tr_decode(p, ws, job);
;   const int kc = tid & 7, nn = tid >> 3;
; #pragma unroll
; __device__ __forceinline__ void p0_transposes(const Params& p, char* smem, int bid, int nb, int jlo, int jhi) {
;   const int tid = vtid();
;   char* ws = p.ws;
;   LAUNDER(ws);
;   float* tileA = (float*)smem;
;   float* tileB = tileA + 64 * 65;
;   float4 c0[4], c1[4], n0[4], n1[4];
;   int j = jlo + bid * 2;
;   if (j < jhi) { tr_load(p, ws, j, tid, c0); tr_load(p, ws, j + 1, tid, c1); }
;   for (; j < jhi; j += 2 * nb) {
.LBB0_154:
	s_and_b64 vcc, exec, s[0:1]
	s_cbranch_vccnz .LBB0_139
	s_add_u32 s48, s4, 0x10e00000
	s_addc_u32 s91, s5, 0
	v_ashrrev_i32_e32 v74, 4, v0
	v_lshlrev_b32_e32 v1, 2, v0
	s_add_u32 s92, s4, 0xe00000
	v_ashrrev_i32_e32 v76, 3, v0
	v_lshlrev_b32_e32 v0, 3, v0
	v_and_b32_e32 v66, 60, v1
	v_lshl_add_u32 v1, v74, 6, v74
	s_addc_u32 s93, s5, 0
	v_and_b32_e32 v0, 56, v0
	v_add_lshl_u32 v75, v1, v66, 2
	s_add_u32 s94, s4, 0xa00000
	v_mul_u32_u24_e32 v1, 0x41, v0
	v_add_u32_e32 v79, 32, v76
	s_addc_u32 s95, s5, 0
	v_and_b32_e32 v77, 31, v76
	v_add_lshl_u32 v78, v1, v76, 2
	v_add_lshl_u32 v80, v1, v79, 2
	v_lshlrev_b32_e32 v68, 1, v0
	s_mov_b32 s97, s77
	s_waitcnt vmcnt(0)
	s_branch .LBB0_174

; __device__ __forceinline__ TrJob tr_decode(const Params& p, char* ws, int job) {
;   TrJob t;
;   int l = job / TJ_PER_LAYER, rj = job % TJ_PER_LAYER;
;   if (rj < 640) {
;     t.src = p.w_in + (size_t)l * 1024 * 2560; t.K = 1024; t.N = 2560; t.kt = rj / 40; t.nt = rj % 40;
;     t.dst = (u16*)(ws + OFF_WINT) + (size_t)l * 2560 * 1024; t.mode = 0;
;   } else if (rj < 896) {
;     rj -= 640;
;     t.src = p.w_out + (size_t)l * 1024 * 1024; t.K = 1024; t.N = 1024; t.kt = rj / 16; t.nt = rj % 16;
;     t.dst = (u16*)(ws + OFF_WOUTT) + (size_t)l * 1024 * 1024; t.mode = 0;
;   } else {
;     rj -= 896;
;     int e = rj / 1536, q = rj % 1536;
;     size_t eo = (size_t)(l * 16 + e);
;     if (q < 512) {
;       t.src = p.w_gate + eo * 1024 * 2048; t.K = 1024; t.N = 2048; t.kt = q / 32; t.nt = q % 32;
;       t.dst = (u16*)(ws + OFF_WGUT) + eo * 4096 * 1024; t.mode = 1;
;     } else if (q < 1024) {
;       q -= 512;
;       t.src = p.w_up + eo * 1024 * 2048; t.K = 1024; t.N = 2048; t.kt = q / 32; t.nt = q % 32;
;       t.dst = (u16*)(ws + OFF_WGUT) + eo * 4096 * 1024; t.mode = 2;
;     } else {
;       q -= 1024;
;       t.src = p.w_down + eo * 2048 * 1024; t.K = 2048; t.N = 1024; t.kt = q / 16; t.nt = q % 16;
;       t.dst = (u16*)(ws + OFF_WDT) + eo * 1024 * 2048; t.mode = 0;
;     }
;   }
; __device__ __forceinline__ void p0_transposes(const Params& p, char* smem, int bid, int nb, int jlo, int jhi) {
;     ...
;   for (; j < jhi; j += 2 * nb) {
;     const int jn = j + 2 * nb;
;     if (jn < jhi) { tr_load(p, ws, jn, tid, n0); tr_load(p, ws, jn + 1, tid, n1); }
;     tr_lds_write(tileA, tid, c0);
;     tr_lds_write(tileB, tid, c1);
;     __syncthreads();
.LBB0_208:
	ds_write2_b32 v75, v16, v17 offset1:1
	ds_write2_b32 v75, v18, v19 offset0:2 offset1:3
	v_add_u32_e32 v16, 0x1040, v75
	ds_write2_b32 v16, v20, v21 offset1:1
	v_add_u32_e32 v16, 0x1048, v75
	ds_write2_b32 v16, v22, v23 offset1:1
	v_add_u32_e32 v16, 0x2080, v75
	ds_write2_b32 v16, v24, v25 offset1:1
	v_add_u32_e32 v16, 0x2088, v75
	ds_write2_b32 v16, v26, v27 offset1:1
	v_add_u32_e32 v16, 0x30c0, v75
	ds_write2_b32 v16, v28, v29 offset1:1
	v_add_u32_e32 v16, 0x30c8, v75
	ds_write2_b32 v16, v30, v31 offset1:1
	v_add_u32_e32 v16, 0x4100, v75
	ds_write2_b32 v16, v48, v49 offset1:1
	v_add_u32_e32 v16, 0x4108, v75
	ds_write2_b32 v16, v50, v51 offset1:1
	v_add_u32_e32 v16, 0x5140, v75
	s_mul_hi_i32 s10, s97, 0x5254e78f
	ds_write2_b32 v16, v52, v53 offset1:1
	v_add_u32_e32 v16, 0x5148, v75
	s_lshr_b32 s11, s10, 31
	s_ashr_i32 s10, s10, 13
	ds_write2_b32 v16, v54, v55 offset1:1
	v_add_u32_e32 v16, 0x6180, v75
	s_add_i32 s54, s10, s11
	ds_write2_b32 v16, v56, v57 offset1:1
	v_add_u32_e32 v16, 0x6188, v75
	s_mul_i32 s10, s54, 0xffff9c80
	ds_write2_b32 v16, v58, v59 offset1:1
	v_add_u32_e32 v16, 0x71c0, v75
	s_add_i32 s10, s97, s10
	ds_write2_b32 v16, v60, v61 offset1:1
	v_add_u32_e32 v16, 0x71c8, v75
	s_cmpk_gt_i32 s10, 0x27f
	s_mov_b64 s[60:61], -1
	ds_write2_b32 v16, v62, v63 offset1:1
	s_waitcnt lgkmcnt(0)
	s_barrier
	s_cbranch_scc0 .LBB0_221
	s_cmpk_gt_u32 s10, 0x37f
	s_cbranch_scc0 .LBB0_218
	s_add_i32 s11, s10, 0xfc80
	s_and_b32 s33, s11, 0xffff
	s_mul_i32 s33, s33, 0xaaab
	s_lshr_b32 s33, s33, 26
	s_mul_i32 s40, s33, 0x600
	s_sub_i32 s11, s11, s40
	s_and_b32 s40, s11, 0xffff
	s_lshl_b32 s11, s54, 4
	s_add_i32 s60, s11, s33
	s_ashr_i32 s61, s60, 31
	s_cmpk_gt_u32 s40, 0x1ff
	s_mov_b64 s[62:63], -1
	s_cbranch_scc0 .LBB0_215
	s_mov_b64 s[52:53], -1
	s_cmpk_gt_u32 s40, 0x3ff
	s_mov_b64 s[56:57], -1
	s_cbranch_scc0 .LBB0_213
	s_add_i32 s11, s40, 0xfffffc00
	s_lshr_b32 s11, s11, 4
	s_and_b32 s33, s40, 15
	s_lshl_b64 s[56:57], s[60:61], 22
	s_add_u32 s58, s48, s56
	s_addc_u32 s59, s91, s57
	s_mov_b64 s[56:57], 0

; __device__ __forceinline__ unsigned pack2(float a, float b) { return (unsigned)f2bf(a) | ((unsigned)f2bf(b) << 16); }
; __device__ __forceinline__ TrJob tr_decode(const Params& p, char* ws, int job) {
;   TrJob t;
;   int l = job / TJ_PER_LAYER, rj = job % TJ_PER_LAYER;
;   if (rj < 640) {
;     t.src = p.w_in + (size_t)l * 1024 * 2560; t.K = 1024; t.N = 2560; t.kt = rj / 40; t.nt = rj % 40;
;     t.dst = (u16*)(ws + OFF_WINT) + (size_t)l * 2560 * 1024; t.mode = 0;
;   } else if (rj < 896) {
;     rj -= 640;
;     t.src = p.w_out + (size_t)l * 1024 * 1024; t.K = 1024; t.N = 1024; t.kt = rj / 16; t.nt = rj % 16;
;     t.dst = (u16*)(ws + OFF_WOUTT) + (size_t)l * 1024 * 1024; t.mode = 0;
;   } else {
;     rj -= 896;
;     int e = rj / 1536, q = rj % 1536;
;     size_t eo = (size_t)(l * 16 + e);
;     if (q < 512) {
;       t.src = p.w_gate + eo * 1024 * 2048; t.K = 1024; t.N = 2048; t.kt = q / 32; t.nt = q % 32;
;       t.dst = (u16*)(ws + OFF_WGUT) + eo * 4096 * 1024; t.mode = 1;
;     } else if (q < 1024) {
;       q -= 512;
;       t.src = p.w_up + eo * 1024 * 2048; t.K = 1024; t.N = 2048; t.kt = q / 32; t.nt = q % 32;
;       t.dst = (u16*)(ws + OFF_WGUT) + eo * 4096 * 1024; t.mode = 2;
;     } else {
;       q -= 1024;
;       t.src = p.w_down + eo * 2048 * 1024; t.K = 2048; t.N = 1024; t.kt = q / 16; t.nt = q % 16;
;       t.dst = (u16*)(ws + OFF_WDT) + eo * 1024 * 2048; t.mode = 0;
;     }
;   }
; __device__ __forceinline__ void tr_store(const Params& p, char* ws, int job, int tid, const float* tile) {
;   TrJob t = tr_decode(p, ws, job);
;   const int kc = tid & 7, nn = tid >> 3;
; #pragma unroll
;   for (int pp = 0; pp < 2; ++pp) {
;     int n = nn + 32 * pp;
;     float v[8];
; #pragma unroll
;     for (int j = 0; j < 8; ++j) v[j] = tile[(kc * 8 + j) * 65 + n];
;     uint4 o;
;     o.x = pack2(v[0], v[1]); o.y = pack2(v[2], v[3]); o.z = pack2(v[4], v[5]); o.w = pack2(v[6], v[7]);
;     int gn = t.nt * 64 + n;
;     int drow = t.mode == 0 ? gn : gu_row(t.mode - 1, gn);
;     *(uint4*)&t.dst[(size_t)drow * t.K + t.kt * 64 + kc * 8] = o;
;   }
; }
.LBB0_223:
	s_lshl_b32 s33, s33, 6
	s_lshl_b32 s10, s11, 6
	v_add_u32_e32 v24, s33, v76
	s_ashr_i32 s11, s10, 31
	v_or_b32_e32 v26, s55, v77
	ds_read2_b32 v[16:17], v78 offset0:65 offset1:130
	v_add_u32_e32 v18, 0x200, v78
	v_add_u32_e32 v22, 0x400, v78
	v_lshlrev_b32_e32 v25, 1, v24
	s_lshl_b64 s[10:11], s[10:11], 1
	ds_read2_b32 v[18:19], v18 offset0:67 offset1:132
	ds_read2_b32 v[22:23], v22 offset0:69 offset1:134
	ds_read_b32 v27, v78
	ds_read_b32 v28, v78 offset:1820
	v_and_or_b32 v25, v25, s90, v26
	s_add_u32 s10, s58, s10
	v_cndmask_b32_e64 v24, v25, v24, s[52:53]
	s_addc_u32 s11, s59, s11
	v_mov_b32_e32 v69, v65
	v_ashrrev_i32_e32 v25, 31, v24
	v_lshl_add_u64 v[20:21], s[10:11], 0, v[68:69]
	v_mul_lo_u32 v29, s56, v25
	v_mul_lo_u32 v30, s57, v24
	v_mad_u64_u32 v[24:25], s[10:11], s56, v24, 0
	v_add3_u32 v25, v25, v29, v30
	s_waitcnt lgkmcnt(4)
	v_and_b32_sdwa v29, v17, v73 dst_sel:DWORD dst_unused:UNUSED_PAD src0_sel:WORD_1 src1_sel:DWORD
	s_waitcnt lgkmcnt(1)
	v_and_b32_sdwa v30, v27, v73 dst_sel:DWORD dst_unused:UNUSED_PAD src0_sel:WORD_1 src1_sel:DWORD
	v_add3_u32 v27, v27, v30, s87
	v_add3_u32 v17, v17, v29, s87
	v_and_b32_sdwa v29, v18, v73 dst_sel:DWORD dst_unused:UNUSED_PAD src0_sel:WORD_1 src1_sel:DWORD
	v_and_b32_sdwa v30, v16, v73 dst_sel:DWORD dst_unused:UNUSED_PAD src0_sel:WORD_1 src1_sel:DWORD
	v_add3_u32 v18, v18, v29, s87
	v_add3_u32 v16, v16, v30, s87
	v_and_b32_e32 v18, 0xffff0000, v18
	v_and_b32_e32 v16, 0xffff0000, v16
	v_or_b32_sdwa v17, v18, v17 dst_sel:DWORD dst_unused:UNUSED_PAD src0_sel:DWORD src1_sel:WORD_1
	v_or_b32_sdwa v16, v16, v27 dst_sel:DWORD dst_unused:UNUSED_PAD src0_sel:DWORD src1_sel:WORD_1
	v_and_b32_sdwa v18, v23, v73 dst_sel:DWORD dst_unused:UNUSED_PAD src0_sel:WORD_1 src1_sel:DWORD
	v_and_b32_sdwa v27, v19, v73 dst_sel:DWORD dst_unused:UNUSED_PAD src0_sel:WORD_1 src1_sel:DWORD
	v_add3_u32 v27, v19, v27, s87
	v_add3_u32 v18, v23, v18, s87
	s_waitcnt lgkmcnt(0)
	v_and_b32_sdwa v19, v28, v73 dst_sel:DWORD dst_unused:UNUSED_PAD src0_sel:WORD_1 src1_sel:DWORD
	v_and_b32_sdwa v23, v22, v73 dst_sel:DWORD dst_unused:UNUSED_PAD src0_sel:WORD_1 src1_sel:DWORD
	v_add3_u32 v19, v28, v19, s87
	v_add3_u32 v22, v22, v23, s87
	v_and_b32_e32 v19, 0xffff0000, v19
	v_and_b32_e32 v22, 0xffff0000, v22
	v_lshl_add_u64 v[24:25], v[24:25], 1, v[20:21]
	v_or_b32_sdwa v19, v19, v18 dst_sel:DWORD dst_unused:UNUSED_PAD src0_sel:DWORD src1_sel:WORD_1
	v_or_b32_sdwa v18, v22, v27 dst_sel:DWORD dst_unused:UNUSED_PAD src0_sel:DWORD src1_sel:WORD_1
	s_waitcnt vmcnt(0)
	global_store_dwordx4 v[24:25], v[16:19], off
	v_add_u32_e32 v24, s33, v79
	v_lshlrev_b32_e32 v25, 1, v24
	ds_read2_b32 v[16:17], v80 offset0:65 offset1:130
	v_add_u32_e32 v18, 0x200, v80
	v_and_or_b32 v25, v25, s90, v26
	ds_read2_b32 v[18:19], v18 offset0:67 offset1:132
	v_cndmask_b32_e64 v24, v25, v24, s[52:53]
	v_ashrrev_i32_e32 v25, 31, v24
	v_mul_lo_u32 v26, s56, v25
	v_mul_lo_u32 v29, s57, v24
	v_mad_u64_u32 v[24:25], s[10:11], s56, v24, 0
	v_add_u32_e32 v22, 0x400, v80
	v_add3_u32 v25, v25, v26, v29
	ds_read2_b32 v[22:23], v22 offset0:69 offset1:134
	ds_read_b32 v27, v78 offset:128
	ds_read_b32 v28, v80 offset:1820
	v_lshl_add_u64 v[20:21], v[24:25], 1, v[20:21]
	s_waitcnt lgkmcnt(0)
	v_and_b32_sdwa v24, v17, v73 dst_sel:DWORD dst_unused:UNUSED_PAD src0_sel:WORD_1 src1_sel:DWORD
	v_add3_u32 v17, v17, v24, s87
	v_and_b32_sdwa v24, v18, v73 dst_sel:DWORD dst_unused:UNUSED_PAD src0_sel:WORD_1 src1_sel:DWORD
	v_add3_u32 v18, v18, v24, s87
	s_add_i32 s10, s97, 1
	v_and_b32_e32 v18, 0xffff0000, v18
	s_mul_hi_i32 s11, s10, 0x5254e78f
	v_or_b32_sdwa v17, v18, v17 dst_sel:DWORD dst_unused:UNUSED_PAD src0_sel:DWORD src1_sel:WORD_1
	v_and_b32_sdwa v18, v23, v73 dst_sel:DWORD dst_unused:UNUSED_PAD src0_sel:WORD_1 src1_sel:DWORD
	v_and_b32_sdwa v24, v19, v73 dst_sel:DWORD dst_unused:UNUSED_PAD src0_sel:WORD_1 src1_sel:DWORD
	s_lshr_b32 s33, s11, 31
	s_ashr_i32 s11, s11, 13
	v_and_b32_sdwa v26, v16, v73 dst_sel:DWORD dst_unused:UNUSED_PAD src0_sel:WORD_1 src1_sel:DWORD
	v_add3_u32 v24, v19, v24, s87
	v_add3_u32 v18, v23, v18, s87
	v_and_b32_sdwa v19, v28, v73 dst_sel:DWORD dst_unused:UNUSED_PAD src0_sel:WORD_1 src1_sel:DWORD
	v_and_b32_sdwa v23, v22, v73 dst_sel:DWORD dst_unused:UNUSED_PAD src0_sel:WORD_1 src1_sel:DWORD
	s_add_i32 s54, s11, s33
	v_and_b32_sdwa v25, v27, v73 dst_sel:DWORD dst_unused:UNUSED_PAD src0_sel:WORD_1 src1_sel:DWORD
	v_add3_u32 v16, v16, v26, s87
	v_add3_u32 v19, v28, v19, s87
	v_add3_u32 v22, v22, v23, s87
	s_mul_i32 s11, s54, 0x6380
	v_add3_u32 v25, v27, v25, s87
	v_and_b32_e32 v16, 0xffff0000, v16
	v_and_b32_e32 v19, 0xffff0000, v19
	v_and_b32_e32 v22, 0xffff0000, v22
	s_sub_i32 s10, s10, s11
	v_or_b32_sdwa v16, v16, v25 dst_sel:DWORD dst_unused:UNUSED_PAD src0_sel:DWORD src1_sel:WORD_1
	v_or_b32_sdwa v19, v19, v18 dst_sel:DWORD dst_unused:UNUSED_PAD src0_sel:DWORD src1_sel:WORD_1
	v_or_b32_sdwa v18, v22, v24 dst_sel:DWORD dst_unused:UNUSED_PAD src0_sel:DWORD src1_sel:WORD_1
	s_cmpk_gt_i32 s10, 0x27f
	s_mov_b64 s[60:61], -1
	global_store_dwordx4 v[20:21], v[16:19], off
	s_cbranch_scc0 .LBB0_236
	s_cmpk_gt_u32 s10, 0x37f
	s_cbranch_scc0 .LBB0_233
	s_add_i32 s11, s10, 0xfc80
	s_and_b32 s33, s11, 0xffff
	s_mul_i32 s33, s33, 0xaaab
	s_lshr_b32 s33, s33, 26
	s_mul_i32 s40, s33, 0x600
	s_sub_i32 s11, s11, s40
	s_and_b32 s40, s11, 0xffff
	s_lshl_b32 s11, s54, 4
	s_add_i32 s60, s11, s33
	s_ashr_i32 s61, s60, 31
	s_cmpk_gt_u32 s40, 0x1ff
	s_mov_b64 s[62:63], -1
	s_cbranch_scc0 .LBB0_230
	s_mov_b64 s[52:53], -1
	s_cmpk_gt_u32 s40, 0x3ff
	s_mov_b64 s[56:57], -1
	s_cbranch_scc0 .LBB0_228
	s_add_i32 s11, s40, 0xfffffc00
	s_lshr_b32 s11, s11, 4
	s_and_b32 s33, s40, 15
	s_lshl_b64 s[56:57], s[60:61], 22
	s_add_u32 s58, s48, s56
	s_addc_u32 s59, s91, s57
	s_mov_b64 s[56:57], 0
